# mixer queue: preprocessing jobs wait on a per-row-tile w_in completion counter (jobs handed out from the last tile down) instead of all queued w_in units; 128 stolen units
# speedup vs baseline: 1.0075x; 1.0075x over previous
.LBB0_671:
	s_or_b64 exec, exec, s[2:3]
	s_waitcnt vmcnt(0)
	v_readfirstlane_b32 s2, v2
	s_mov_b64 s[8:9], s[72:73]
	s_nop 0
	v_add_u32_e32 v0, s2, v0
	v_add_u32_e32 v2, 0x80, v0
	v_cmp_lt_i32_e32 vcc, 0xff, v0
	s_nop 1
	v_cndmask_b32_e32 v0, v0, v2, vcc
	v_cmp_gt_i32_e32 vcc, 0x288, v0
	v_cmp_le_i32_e64 s[2:3], s85, v0
	s_or_b64 s[4:5], vcc, s[2:3]
	s_nor_b64 s[10:11], s[4:5], s[72:73]
	s_and_saveexec_b64 s[4:5], s[10:11]
	s_cbranch_execz .LBB0_686
	s_mov_b32 s10, 0x1000000
	s_branch .LBB0_675

.LBB0_799:
	s_waitcnt vmcnt(4)
	s_sub_i32 s43, 0x407, s43
	s_add_i32 s100, s43, 0xfffffe80
	s_lshr_b32 s100, s100, 2
	s_cmp_lt_u32 s100, 32
	s_cselect_b32 s101, 6, 2
	s_cmp_lt_u32 s100, 64
	s_cselect_b32 s101, s101, 0
	s_cmp_eq_u32 s101, 0
	s_cbranch_scc1 .Lpw_done
	s_mul_i32 s100, s100, 48
	s_addk_i32 s100, 0x1000
	s_mov_b32 vcc_lo, 0
.Lpw_loop:
	v_mov_b32_e32 v0, s100
	global_load_dword v0, v0, s[90:91] sc1
	s_waitcnt vmcnt(0)
	v_readfirstlane_b32 vcc_hi, v0
	s_nop 3
	s_cmp_ge_u32 vcc_hi, s101
	s_cbranch_scc1 .Lpw_acq
	s_sleep 2
	s_add_i32 vcc_lo, vcc_lo, 1
	s_cmp_lt_u32 vcc_lo, 0x1000000
	s_cbranch_scc1 .Lpw_loop

.Lpw_done:
	v_mov_b32_e32 v40, v156
	v_mov_b32_e32 v0, s23
	s_waitcnt vmcnt(0)
	v_and_b32_e32 v17, 63, v40
	v_mov_b32_e32 v2, s21
	v_cmp_gt_u32_e64 s[2:3], 32, v17
	v_readlane_b32 s4, v254, 34
	v_lshlrev_b32_e32 v19, 3, v40
	v_cndmask_b32_e64 v3, v0, v2, s[2:3]
	v_mov_b32_e32 v0, s22
	v_mov_b32_e32 v2, s20
	v_cndmask_b32_e64 v2, v0, v2, s[2:3]
	v_readlane_b32 s5, v254, 35
	v_and_b32_e32 v0, 56, v19
	v_lshlrev_b32_e32 v0, 2, v0
	v_lshl_add_u64 v[2:3], s[4:5], 2, v[2:3]
	v_lshl_add_u64 v[6:7], v[2:3], 0, v[0:1]
	v_bitop3_b32 v0, v19, 16, 56 bitop3:0x6c
	v_lshlrev_b32_e32 v0, 2, v0
	v_lshl_add_u64 v[10:11], v[2:3], 0, v[0:1]
	global_load_dwordx4 v[2:5], v[6:7], off offset:16
	s_nop 0
	global_load_dwordx4 v[6:9], v[6:7], off
	s_nop 0
	global_load_dwordx3 v[14:16], v[10:11], off offset:20
	global_load_dword v18, v[10:11], off
	s_nop 0
	global_load_dwordx4 v[10:13], v[10:11], off offset:4
	v_lshlrev_b32_e32 v0, 3, v17
	v_readlane_b32 s8, v254, 53
	v_cmp_lt_u32_e64 s[4:5], 47, v17
	v_cmp_gt_u32_e64 s[6:7], 48, v17
	v_add_u32_e32 v20, s8, v0
	v_add_u32_e32 v0, s84, v0
	v_mov_b32_e32 v21, 0
	v_cndmask_b32_e64 v28, v20, v0, s[2:3]
	v_mov_b32_e32 v20, 0
	s_and_saveexec_b64 s[8:9], s[6:7]
	s_cbranch_execz .LBB0_801
	v_mov_b32_e32 v0, s27
	v_mov_b32_e32 v20, s25
	v_cndmask_b32_e64 v23, v0, v20, s[2:3]
	v_mov_b32_e32 v0, s26
	v_mov_b32_e32 v20, s24
	v_cndmask_b32_e64 v22, v0, v20, s[2:3]
	v_ashrrev_i32_e32 v29, 31, v28
	v_lshl_add_u64 v[22:23], v[28:29], 2, v[22:23]
	global_load_dword v20, v[22:23], off

.Lq_done:
	s_mul_hi_u32 s100, s43, 0xaaaaaaab
	s_lshr_b32 s100, s100, 2
	s_mul_i32 s100, s100, 48
	s_addk_i32 s100, 0x1000
	s_mul_hi_i32 s2, s43, 0x2aaaaaab
	v_lshlrev_b32_e32 v0, 4, v13
	v_add_u32_e32 v2, 0x2000, v0
	v_ashrrev_i32_e32 v3, 31, v2
	v_lshrrev_b32_e32 v3, 22, v3
	v_add_u32_e32 v3, v2, v3
	v_ashrrev_i32_e32 v10, 10, v3
	v_mul_i32_i24_e32 v3, 0x400, v10
	v_sub_u32_e32 v2, v2, v3
	v_lshrrev_b32_e32 v3, 4, v2
	s_lshr_b32 s3, s2, 31
	v_bitop3_b32 v2, v3, v2, 32 bitop3:0x6c
	s_add_i32 s2, s2, s3
	v_ashrrev_i32_e32 v3, 31, v2
	s_mul_i32 s3, s2, -6
	v_lshrrev_b32_e32 v3, 26, v3
	s_add_i32 s3, s3, s43
	v_add_u32_e32 v3, v2, v3
	v_lshlrev_b32_e32 v4, 3, v10
	s_add_i32 s4, s3, 5
	v_ashrrev_i32_e32 v11, 6, v3
	v_and_b32_e32 v4, -16, v4
	s_cmp_lt_i32 s3, 4
	v_add_u32_e32 v4, v11, v4
	s_cselect_b32 s4, s3, s4
	v_and_b32_e32 v5, 3, v11
	s_mov_b32 s3, 0x1fffe0
	v_lshrrev_b32_e32 v6, 2, v4
	v_lshlrev_b32_e32 v7, 1, v4
	v_and_b32_e32 v3, 0xc0, v3
	v_and_or_b32 v5, v4, s3, v5
	v_and_b32_e32 v6, 4, v6
	v_and_b32_e32 v7, 24, v7
	v_sub_u32_e32 v2, v2, v3
	v_or3_b32 v5, v5, v6, v7
	v_lshlrev_b32_e32 v6, 5, v10
	v_ashrrev_i16_sdwa v2, v167, sext(v2) dst_sel:DWORD dst_unused:UNUSED_PAD src0_sel:DWORD src1_sel:BYTE_0
	v_and_b32_e32 v6, 32, v6
	v_bfe_i32 v12, v2, 0, 16
	v_add_lshl_u32 v2, v6, v12, 1
	v_lshl_add_u32 v134, v5, 11, v2
	v_lshl_add_u32 v136, v4, 11, v2
	v_bfe_i32 v2, v13, 27, 1
	v_lshrrev_b32_e32 v2, 22, v2
	v_add_u32_e32 v2, v0, v2
	v_and_b32_e32 v2, 0xfffffc00, v2
	v_sub_u32_e32 v0, v0, v2
	v_lshrrev_b32_e32 v2, 4, v0
	v_bitop3_b32 v2, v2, v0, 32 bitop3:0x6c
	v_ashrrev_i32_e32 v0, 31, v0
	v_lshrrev_b32_e32 v0, 26, v0
	v_add_u32_e32 v0, v2, v0
	v_ashrrev_i32_e32 v14, 6, v0
	v_ashrrev_i32_e32 v0, 31, v13
	v_lshrrev_b32_e32 v0, 26, v0
	v_add_u32_e32 v0, v13, v0
	v_ashrrev_i32_e32 v15, 6, v0
	v_lshlrev_b32_e32 v0, 3, v15
	v_and_b32_e32 v0, -16, v0
	v_add_u32_e32 v3, v14, v0
	v_and_b32_e32 v0, 3, v14
	v_lshrrev_b32_e32 v4, 2, v3
	v_lshlrev_b32_e32 v5, 1, v3
	v_and_or_b32 v0, v3, s3, v0
	v_and_b32_e32 v4, 4, v4
	v_and_b32_e32 v5, 24, v5
	v_readfirstlane_b32 s34, v13
	v_or3_b32 v0, v0, v4, v5
	v_mul_i32_i24_e32 v5, 64, v14
	s_ashr_i32 s14, s34, 6
	v_sub_u32_e32 v2, v2, v5
	s_ashr_i32 s3, s2, 31
	s_ashr_i32 s5, s4, 31
	s_ashr_i32 s15, s34, 8
	s_lshl_b32 s35, s14, 10
	v_lshlrev_b32_e32 v4, 5, v15
	v_ashrrev_i16_sdwa v2, v167, sext(v2) dst_sel:DWORD dst_unused:UNUSED_PAD src0_sel:DWORD src1_sel:BYTE_0
	s_lshl_b64 s[12:13], s[2:3], 19
	s_lshl_b64 s[10:11], s[4:5], 19
	v_and_b32_e32 v4, 32, v4
	v_bfe_i32 v16, v2, 0, 16
	s_add_u32 s6, s92, s10
	v_add_lshl_u32 v2, v4, v16, 1
	s_addc_u32 s7, s96, s11
	s_add_i32 s3, s35, 0
	v_lshl_add_u32 v0, v0, 11, v2
	s_add_i32 m0, s3, 0x10000
	v_lshl_add_u32 v138, v3, 11, v2
	global_load_lds_dwordx4 v0, s[6:7]
	s_add_i32 m0, s3, 0x12000
	s_add_u32 s8, s6, 0x40000
	global_load_lds_dwordx4 v134, s[6:7]
	s_addc_u32 s9, s7, 0
	s_add_i32 m0, s3, 0x14000
	v_mov_b32_e32 v135, v1
	global_load_lds_dwordx4 v0, s[8:9]
	s_add_i32 m0, s3, 0x16000
	v_mov_b32_e32 v139, v1
	global_load_lds_dwordx4 v134, s[8:9]
	s_add_u32 s8, s86, s12
	s_addc_u32 s9, s87, s13
	s_add_i32 s5, s3, 0x2000
	s_mov_b32 m0, s3
	s_add_u32 s52, s8, 0x40000
	global_load_lds_dwordx4 v138, s[8:9]
	s_mov_b32 m0, s5
	s_addc_u32 s53, s9, 0
	s_add_i32 s43, s3, 0x4000
	global_load_lds_dwordx4 v136, s[8:9]
	s_mov_b32 m0, s43
	s_add_i32 s44, s3, 0x6000
	global_load_lds_dwordx4 v138, s[52:53]
	s_mov_b32 m0, s44
	v_mov_b32_e32 v137, v1
	global_load_lds_dwordx4 v136, s[52:53]
	v_lshl_add_u64 v[8:9], s[6:7], 0, v[0:1]
	v_lshl_add_u64 v[6:7], s[6:7], 0, v[134:135]
	v_lshl_add_u64 v[4:5], s[8:9], 0, v[138:139]
	s_cmp_lg_u32 s15, 1
	v_lshl_add_u64 v[2:3], s[8:9], 0, v[136:137]
	s_cbranch_scc1 .LBB0_837
	s_barrier

.LBB0_961:
	s_barrier
	s_waitcnt vmcnt(0)
	v_mov_b32_e32 v0, v156
	s_waitcnt vmcnt(0)
	s_barrier
	s_nop 0
	v_cmp_eq_u32_e32 vcc, 0, v0
	s_and_saveexec_b64 s[2:3], vcc
	s_xor_b64 s[2:3], exec, s[2:3]
	s_cbranch_execz .LBB0_665
	s_mov_b64 s[4:5], exec
	buffer_wbl2 sc1
	s_waitcnt vmcnt(0)
	v_mbcnt_lo_u32_b32 v0, s4, 0
	v_mbcnt_hi_u32_b32 v0, s5, v0
	v_cmp_eq_u32_e32 vcc, 0, v0
	s_and_saveexec_b64 s[6:7], vcc
	s_xor_b64 s[6:7], exec, s[6:7]
	s_cbranch_execz .LBB0_664
	s_bcnt1_i32_b64 s4, s[4:5]
	v_mov_b32_e32 v0, s4
	global_atomic_add v1, v0, s[90:91] offset:192
	v_mov_b32_e32 v2, s100
	global_atomic_add v2, v0, s[90:91]
	s_branch .LBB0_664
